# attention: T5 bias table for all heads built once per phase in LDS; per-item table fill (global load on the critical path of waves 0-2) removed
# baseline (speedup 1.0000x reference)
;     __device__ __forceinline__ bf16_t* bfp(size_t off) const { return (bf16_t*)(ws + off); }
; __device__ __forceinline__ void attn_fetch(const Ctx& C, int it, u32x4 (&kv)[4], u32x4 (&vv)[4], u32x4 (&qv)[2]) {
;     const int tid = C.tid;
;     const int b = it / 384, rem = it % 384, hq = rem >> 5, kk = rem & 31, g = hq >> 2, dil = 1 << (2 * g), n = SEQ / dil, nblk = 32 / dil, r = kk / nblk, jb = kk % nblk;
;     const bf16_t* pd = C.bfp(OFF_PROJD);
; #pragma unroll
;     for (int k = 0; k < 4; ++k) { const int id = tid + NTHR * k, cidx = id >> 3, ch = id & 7, ik = 128 * jb - 64 + cidx;
;         kv[k] = (u32x4){0u, 0u, 0u, 0u}; vv[k] = (u32x4){0u, 0u, 0u, 0u};
;         if (ik >= 0 && ik < n) { const bf16_t* row = pd + (size_t)(b * SEQ + r + dil * ik) * 2304; kv[k] = *(const u32x4*)(row + 768 + hq * 64 + ch * 8); vv[k] = *(const u32x4*)(row + 1536 + hq * 64 + ch * 8); } }
; #pragma unroll
;     for (int k = 0; k < 2; ++k) { const int id = tid + NTHR * k, a = id >> 3, ch = id & 7;
;         qv[k] = *(const u32x4*)(pd + (size_t)(b * SEQ + r + dil * (128 * jb + a)) * 2304 + hq * 64 + ch * 8); }
; __device__ __forceinline__ void attn_item(const Ctx& C, int it, int itn, u32x4 (&kv)[4], u32x4 (&vv)[4], u32x4 (&qv)[2]) {
;     ...
;     if (tid < 129) { const int rel = (tid - 64) * dil, na = rel < 0 ? -rel : rel;
;         int bk = na < 8 ? na : 8 + (na >= 15) + (na >= 27) + (na >= 50) + (na >= 91) + (na >= 166) + (na >= 305) + (na >= 559);
;         if (rel > 0) bk += 16;
;         bt[tid] = C.P->in[21][bk * 12 + hq]; }
.LBB0_334:
	s_or_b64 exec, exec, s[0:1]
	s_waitcnt lgkmcnt(0)
	v_mov_b32_e32 v0, v224
	s_mov_b64 s[0:1], 0
	s_barrier
	v_readlane_b32 s4, v251, 46
	v_readlane_b32 s5, v251, 47
	s_mov_b32 s6, 0xfe04
	s_movk_i32 s7, 0x60c
	s_mov_b32 s12, 4
	v_mov_b32_e32 v0, v224
	s_mov_b64 s[8:9], exec
.Lmy_bt_loop:
	v_cmp_gt_u32_e32 vcc, s7, v0
	s_and_b64 exec, s[8:9], vcc
	s_cbranch_execz .Lmy_bt_done
	v_mul_u32_u24_e32 v1, s6, v0
	v_lshrrev_b32_e32 v1, 23, v1
	v_mul_u32_u24_e32 v2, 0x81, v1
	v_sub_u32_e32 v2, v0, v2
	v_lshrrev_b32_e32 v3, 2, v1
	v_lshlrev_b32_e32 v3, 1, v3
	v_add_u32_e32 v4, 0xffffffc0, v2
	v_lshlrev_b32_e32 v4, v3, v4
	v_sub_u32_e32 v5, 0, v4
	v_max_i32_e32 v5, v4, v5
	v_mov_b32_e32 v6, 8
	v_cmp_lt_u32_e32 vcc, 14, v5
	s_nop 1
	v_addc_co_u32_e32 v6, vcc, 0, v6, vcc
	v_cmp_lt_u32_e32 vcc, 26, v5
	s_nop 1
	v_addc_co_u32_e32 v6, vcc, 0, v6, vcc
	v_cmp_lt_u32_e32 vcc, 49, v5
	s_nop 1
	v_addc_co_u32_e32 v6, vcc, 0, v6, vcc
	v_cmp_lt_u32_e32 vcc, 0x5a, v5
	s_nop 1
	v_addc_co_u32_e32 v6, vcc, 0, v6, vcc
	v_cmp_lt_u32_e32 vcc, 0xa5, v5
	s_nop 1
	v_addc_co_u32_e32 v6, vcc, 0, v6, vcc
	v_cmp_lt_u32_e32 vcc, 0x130, v5
	s_nop 1
	v_addc_co_u32_e32 v6, vcc, 0, v6, vcc
	v_cmp_lt_u32_e32 vcc, 0x22e, v5
	s_nop 1
	v_addc_co_u32_e32 v6, vcc, 0, v6, vcc
	v_cmp_gt_u32_e32 vcc, 8, v5
	s_nop 1
	v_cndmask_b32_e32 v6, v6, v5, vcc
	v_cmp_lt_i32_e32 vcc, 0, v4
	s_nop 1
	v_cndmask_b32_e64 v7, 0, 16, vcc
	v_add_u32_e32 v6, v6, v7
	v_mad_u32_u24 v6, v6, 12, v1
	v_lshlrev_b32_e32 v6, 2, v6
	global_load_dword v7, v6, s[4:5]
	v_lshlrev_b32_e32 v8, 2, v0
	v_add_u32_e32 v8, 0x17000, v8
	s_waitcnt vmcnt(0)
	ds_write_b32 v8, v7
	v_add_u32_e32 v0, 0x200, v0
	s_sub_i32 s12, s12, 1
	s_cmp_lg_u32 s12, 0
	s_cbranch_scc1 .Lmy_bt_loop
.Lmy_bt_done:
	s_mov_b64 exec, s[8:9]
	s_waitcnt lgkmcnt(0)
	v_mov_b32_e32 v40, v224
	s_mov_b64 s[0:1], 0
	s_add_u32 s36, s24, s0
	v_lshlrev_b32_e32 v41, 3, v40
	v_ashrrev_i32_e32 v92, 3, v40
	v_readlane_b32 s0, v253, 22
	s_addc_u32 s40, s25, s1
	v_and_b32_e32 v4, 56, v41
	v_add_u32_e32 v12, s0, v92
	v_readlane_b32 s0, v253, 20
	v_mov_b32_e32 v2, v65
	v_mov_b32_e32 v3, v65
	s_add_u32 s42, s36, 0xe000000
	v_cmp_lt_i32_e32 vcc, -1, v12
	v_cmp_gt_i32_e64 s[4:5], s0, v12
	v_mov_b32_e32 v0, v65
	v_mov_b32_e32 v1, v65
	v_lshlrev_b32_e32 v78, 1, v4
	v_mov_b64_e32 v[10:11], v[2:3]
	v_mov_b64_e32 v[6:7], v[2:3]
	v_readfirstlane_b32 s6, v40
	s_addc_u32 s43, s40, 0
	s_and_b64 s[4:5], vcc, s[4:5]
	v_mov_b64_e32 v[8:9], v[0:1]
	v_mov_b64_e32 v[4:5], v[0:1]
	s_and_saveexec_b64 s[0:1], s[4:5]
	s_cbranch_execz .LBB0_336
	v_readlane_b32 s4, v253, 19
	v_mov_b32_e32 v79, v65
	s_nop 0
	v_lshlrev_b32_e32 v4, s4, v12
	v_readlane_b32 s4, v253, 16
	s_nop 1
	v_add_u32_e32 v6, s4, v4
	v_mov_b64_e32 v[4:5], s[42:43]
	v_mad_i64_i32 v[4:5], s[4:5], v6, s92, v[4:5]
	v_readlane_b32 s4, v253, 17
	v_readlane_b32 s5, v253, 18
	s_nop 1
	v_lshl_add_u64 v[4:5], s[4:5], 1, v[4:5]
	v_lshl_add_u64 v[8:9], v[4:5], 0, v[78:79]
	global_load_dwordx4 v[4:7], v[8:9], off offset:1536
	s_nop 0
	global_load_dwordx4 v[8:11], v[8:9], off offset:3072

;     __device__ __forceinline__ bf16_t* bfp(size_t off) const { return (bf16_t*)(ws + off); }
; __device__ __forceinline__ void attn_item(const Ctx& C, int it, int itn, u32x4 (&kv)[4], u32x4 (&vv)[4], u32x4 (&qv)[2]) {
;     ...
;     const int b = it / 384, rem = it % 384, hq = rem >> 5, kk = rem & 31, g = hq >> 2, dil = 1 << (2 * g), n = SEQ / dil, nblk = 32 / dil, r = kk / nblk, jb = kk % nblk;
;     bf16_t* Ks = (bf16_t*)C.lds; bf16_t* Qs = Ks + 256 * 72; bf16_t* Vs = Qs + 128 * 72; float* bt = (float*)(Vs + 256 * 72);
;     bf16_t* pd = C.bfp(OFF_PROJD);
;     if (tid < 129) { const int rel = (tid - 64) * dil, na = rel < 0 ? -rel : rel;
;         int bk = na < 8 ? na : 8 + (na >= 15) + (na >= 27) + (na >= 50) + (na >= 91) + (na >= 166) + (na >= 305) + (na >= 559);
;         if (rel > 0) bk += 16;
;         bt[tid] = C.P->in[21][bk * 12 + hq]; }
;     {
; #pragma unroll
;         for (int k = 0; k < 4; ++k) { const int id = tid + NTHR * k, cidx = id >> 3, ch = id & 7;
;             *(u32x4*)(Ks + cidx * 72 + ch * 8) = kv[k];
;             *(u32x4*)(Vs + cidx * 72 + ch * 8) = vv[k]; }
; #pragma unroll
;         for (int k = 0; k < 2; ++k) { const int id = tid + NTHR * k, a = id >> 3, ch = id & 7; *(u32x4*)(Qs + a * 72 + ch * 8) = qv[k]; }
;     }
;     if (itn < 3072) attn_fetch(C, itn, kv, vv, qv);
.LBB0_345:
	s_mul_hi_i32 s0, s50, 0x2aaaaaab
	s_lshr_b32 s1, s0, 31
	s_ashr_i32 s51, s0, 6
	s_add_i32 s51, s51, s1
	s_mul_i32 s0, s51, 0xfffffe80
	s_add_i32 s36, s50, s0
	s_ashr_i32 s40, s36, 7
	s_ashr_i32 s41, s36, 5
	s_lshl_b32 s52, s40, 1
	s_add_i32 s50, s50, s26
	s_cmpk_gt_i32 s50, 0xbff
	s_cselect_b64 s[44:45], -1, 0
	s_and_b64 vcc, exec, s[44:45]
	s_waitcnt vmcnt(3)
	ds_write_b128 v82, v[4:7]
	s_waitcnt vmcnt(2)
	ds_write_b128 v82, v[8:11] offset:55296
	ds_write_b128 v84, v[12:15]
	ds_write_b128 v84, v[0:3] offset:55296
	ds_write_b128 v86, v[16:19]
	ds_write_b128 v86, v[20:23] offset:55296
	ds_write_b128 v88, v[24:27]
	ds_write_b128 v88, v[28:31] offset:55296
	s_waitcnt vmcnt(0)
	ds_write_b128 v82, v[36:39] offset:36864
	ds_write_b128 v84, v[32:35] offset:36864
	s_cbranch_vccnz .LBB0_359
	s_mul_hi_i32 s0, s50, 0x2aaaaaab
	s_lshr_b32 s1, s0, 31
	s_ashr_i32 s0, s0, 6
	s_add_i32 s0, s0, s1
	s_mul_i32 s1, s0, 0xfffffe80
	s_add_i32 s1, s50, s1
	s_and_b32 s46, s1, 31
	s_ashr_i32 s1, s1, 6
	s_and_b32 s48, s1, -2
	s_lshr_b32 s1, 32, s48
	s_add_i32 s1, s1, -1
	s_and_b32 s1, s1, s46
	s_lshl_b32 s49, s1, 7
	s_sub_i32 s47, 5, s48
	s_sub_i32 s69, s49, 64
	s_lshl_b32 s1, s0, 12
	s_mulk_i32 s0, 0xfd00
	s_lshr_b32 s68, 0x1000, s48
	s_lshr_b32 s47, s46, s47
	s_add_i32 s0, s67, s0
	v_add_u32_e32 v12, s69, v92
	v_mov_b32_e32 v2, v65
	v_mov_b32_e32 v3, v65
	s_or_b32 s53, s47, s1
	s_and_b32 s46, s0, 0xffffffc0
	v_cmp_lt_i32_e64 s[0:1], -1, v12
	v_cmp_gt_i32_e32 vcc, s68, v12
	v_mov_b32_e32 v0, v65
	v_mov_b32_e32 v1, v65
	v_mov_b64_e32 v[10:11], v[2:3]
	v_mov_b64_e32 v[6:7], v[2:3]
	s_ashr_i32 s47, s46, 31
	s_and_b64 vcc, s[0:1], vcc
	v_mov_b64_e32 v[8:9], v[0:1]
	v_mov_b64_e32 v[4:5], v[0:1]
	s_and_saveexec_b64 s[0:1], vcc
	s_cbranch_execz .LBB0_352
	v_lshlrev_b32_e32 v4, s48, v12
	v_add_u32_e32 v6, s53, v4
	v_mov_b64_e32 v[4:5], s[42:43]
	v_mad_i64_i32 v[4:5], vcc, v6, s66, v[4:5]
	v_lshl_add_u64 v[4:5], s[46:47], 1, v[4:5]
	v_mov_b32_e32 v79, v65
	v_lshl_add_u64 v[8:9], v[4:5], 0, v[78:79]
	global_load_dwordx4 v[4:7], v[8:9], off offset:1536
	s_nop 0
	global_load_dwordx4 v[8:11], v[8:9], off offset:3072

; __device__ __forceinline__ void attn_item(const Ctx& C, int it, int itn, u32x4 (&kv)[4], u32x4 (&vv)[4], u32x4 (&qv)[2]) {
;     ...
;     const int fr = lane & 15, quad = lane >> 4;
;     bf16x8 qf[2];
;     qf[0] = *(const bf16x8*)(Qs + (16 * w + fr) * 72 + 8 * quad); qf[1] = *(const bf16x8*)(Qs + (16 * w + fr) * 72 + 32 + 8 * quad);
;     f32x4 sc[9];
; #pragma unroll
;     for (int kt = 0; kt < 9; ++kt) { const bf16_t* kr = Ks + (16 * (w + kt) + fr) * 72 + 8 * quad;
;         const bf16x8 k0 = *(const bf16x8*)kr, k1 = *(const bf16x8*)(kr + 32);
;         f32x4 z4 = {0.f, 0.f, 0.f, 0.f};
;         z4 = __builtin_amdgcn_mfma_f32_16x16x32_bf16(k0, qf[0], z4, 0, 0, 0);
;         sc[kt] = __builtin_amdgcn_mfma_f32_16x16x32_bf16(k1, qf[1], z4, 0, 0, 0); }
;     const int a = 16 * w + fr;
;     float mx = -1e30f;
; #pragma unroll
;     for (int kt = 0; kt < 9; ++kt)
; #pragma unroll
;         for (int rg = 0; rg < 4; ++rg) { const int cidx = 16 * (w + kt) + 4 * quad + rg, rel = cidx - 64 - a, ik = 128 * jb - 64 + cidx;
;             const bool valid = (rel >= -64) && (rel <= 64) && (ik >= 0) && (ik < n);
;             const int bi = rel < -64 ? 0 : (rel > 64 ? 128 : rel + 64);
;             const float s = valid ? sc[kt][rg] * 0.125f + bt[bi] : -1e30f;
;             sc[kt][rg] = s; mx = fmaxf(mx, s); }
.LBB0_359:
	s_waitcnt lgkmcnt(0)
	s_barrier
	v_and_b32_e32 v100, 15, v224
	v_bfe_u32 v98, v224, 4, 2
	v_lshlrev_b32_e32 v98, 2, v98
	v_sub_u32_e32 v98, v98, v100
	s_mul_i32 s0, s41, 0x204
	s_add_i32 s0, s0, 0x17000
	v_lshl_add_u32 v98, v98, 2, s0
	ds_read_b32 v212, v98 offset:0
	ds_read_b32 v213, v98 offset:4
	ds_read_b32 v214, v98 offset:8
	ds_read_b32 v215, v98 offset:12
	ds_read_b32 v223, v98 offset:64
	ds_read_b32 v228, v98 offset:68
	ds_read_b32 v229, v98 offset:72
	ds_read_b32 v230, v98 offset:76
	ds_read_b32 v231, v98 offset:128
	ds_read_b32 v232, v98 offset:132
	ds_read_b32 v233, v98 offset:136
	ds_read_b32 v234, v98 offset:140
	ds_read_b32 v235, v98 offset:192
	ds_read_b32 v236, v98 offset:196
	ds_read_b32 v237, v98 offset:200
	ds_read_b32 v238, v98 offset:204
	ds_read_b32 v240, v98 offset:256
	ds_read_b32 v241, v98 offset:260
	ds_read_b32 v242, v98 offset:264
	ds_read_b32 v243, v98 offset:268
	ds_read_b32 v244, v98 offset:320
	ds_read_b32 v245, v98 offset:324
	ds_read_b32 v246, v98 offset:328
	ds_read_b32 v247, v98 offset:332
	ds_read_b32 v248, v98 offset:384
	ds_read_b32 v249, v98 offset:388
	ds_read_b32 v250, v98 offset:392
	ds_read_b128 v[40:43], v85 offset:36864
	ds_read_b128 v[194:197], v85 offset:36928
	ds_read_b128 v[44:47], v87
	ds_read_b128 v[48:51], v87 offset:64
	s_waitcnt lgkmcnt(1)
	v_mfma_f32_16x16x32_bf16 v[44:47], v[44:47], v[40:43], 0
	s_lshr_b32 s0, 32, s52
	s_and_b32 s47, s36, 31
	s_add_i32 s0, s0, -1
	s_waitcnt lgkmcnt(0)
	v_mfma_f32_16x16x32_bf16 v[74:77], v[48:51], v[194:197], v[44:47]
	s_nop 2
	ds_read_b128 v[44:47], v173
	ds_read_b128 v[48:51], v173 offset:64
	s_and_b32 s0, s0, s47
	s_lshl_b32 s46, s0, 7
	s_waitcnt lgkmcnt(1)
	v_mfma_f32_16x16x32_bf16 v[44:47], v[44:47], v[40:43], 0
	s_sub_i32 s48, s46, 64
	v_add_u32_e32 v64, s48, v89
	v_readlane_b32 s0, v255, 7
	s_waitcnt lgkmcnt(0)
	v_mfma_f32_16x16x32_bf16 v[70:73], v[48:51], v[194:197], v[44:47]
	s_nop 2
	ds_read_b128 v[44:47], v174
	ds_read_b128 v[48:51], v174 offset:64
	s_lshr_b32 s53, 0x1000, s52
	v_cmp_lt_i32_e32 vcc, -1, v64
	s_waitcnt lgkmcnt(1)
	v_mfma_f32_16x16x32_bf16 v[44:47], v[44:47], v[40:43], 0
	v_readlane_b32 s1, v255, 8
	s_and_b64 s[0:1], s[0:1], vcc
	v_cmp_gt_i32_e32 vcc, s53, v64
	s_waitcnt lgkmcnt(0)
	v_mfma_f32_16x16x32_bf16 v[66:69], v[48:51], v[194:197], v[44:47]
	s_nop 2
	ds_read_b128 v[44:47], v175
	ds_read_b128 v[48:51], v175 offset:64
	s_and_b64 s[68:69], s[0:1], vcc
	s_waitcnt lgkmcnt(1)
	v_mfma_f32_16x16x32_bf16 v[44:47], v[44:47], v[40:43], 0
	s_waitcnt lgkmcnt(0)
	v_mfma_f32_16x16x32_bf16 v[60:63], v[48:51], v[194:197], v[44:47]
	s_nop 5
	ds_read_b128 v[44:47], v176
	ds_read_b128 v[48:51], v176 offset:64
	s_waitcnt lgkmcnt(1)
	v_mfma_f32_16x16x32_bf16 v[44:47], v[44:47], v[40:43], 0
	s_waitcnt lgkmcnt(0)
	v_mfma_f32_16x16x32_bf16 v[56:59], v[48:51], v[194:197], v[44:47]
	s_nop 5
	ds_read_b128 v[44:47], v177
	ds_read_b128 v[48:51], v177 offset:64
	s_waitcnt lgkmcnt(1)
	v_mfma_f32_16x16x32_bf16 v[44:47], v[44:47], v[40:43], 0
	s_waitcnt lgkmcnt(0)
	v_mfma_f32_16x16x32_bf16 v[52:55], v[48:51], v[194:197], v[44:47]
	s_nop 5
	ds_read_b128 v[44:47], v183
	ds_read_b128 v[48:51], v183 offset:64
	s_waitcnt lgkmcnt(1)
	v_mfma_f32_16x16x32_bf16 v[44:47], v[44:47], v[40:43], 0
	s_waitcnt lgkmcnt(0)
	v_mfma_f32_16x16x32_bf16 v[48:51], v[48:51], v[194:197], v[44:47]
	s_nop 5
	ds_read_b128 v[44:47], v192
	ds_read_b128 v[198:201], v192 offset:64
	s_waitcnt lgkmcnt(1)
	v_mfma_f32_16x16x32_bf16 v[44:47], v[44:47], v[40:43], 0
	s_waitcnt lgkmcnt(0)
	v_mfma_f32_16x16x32_bf16 v[44:47], v[198:201], v[194:197], v[44:47]
	ds_read_b128 v[198:201], v193
	ds_read_b128 v[202:205], v193 offset:64
	s_waitcnt lgkmcnt(1)
	v_mfma_f32_16x16x32_bf16 v[40:43], v[198:201], v[40:43], 0
	s_waitcnt lgkmcnt(0)
	v_mfma_f32_16x16x32_bf16 v[40:43], v[202:205], v[194:197], v[40:43]
	v_lshrrev_b32_e32 v178, 6, v224
	v_lshlrev_b32_e32 v178, 4, v178
	v_and_b32_e32 v179, 15, v224
	v_add_u32_e32 v179, v178, v179
	s_sub_i32 s0, 0, s48
	v_max_i32_e32 v180, s0, v179
	s_sub_i32 s1, s53, s48
	s_add_i32 s1, s1, -1
	v_add_u32_e32 v179, 0x80, v179
	v_min_i32_e32 v181, s1, v179
	v_bfe_u32 v179, v224, 4, 2
	v_lshl_add_u32 v178, v179, 2, v178
	v_sub_u32_e32 v188, v178, v180
	v_sub_u32_e32 v189, v181, v180
	v_mov_b32_e32 v179, 0xf149f2ca
	v_add_u32_e32 v190, 0, v188
	v_cmp_ge_u32_e32 vcc, v189, v190
	v_fmac_f32_e32 v212, 0x3e000000, v74
	v_add_u32_e32 v191, 1, v188
	v_cndmask_b32_e32 v195, v179, v212, vcc
	ds_read_b32 v212, v98 offset:396
	v_cmp_ge_u32_e32 vcc, v189, v191
	v_fmac_f32_e32 v213, 0x3e000000, v75
	v_add_u32_e32 v190, 2, v188
	v_cndmask_b32_e32 v91, v179, v213, vcc
	ds_read_b32 v213, v98 offset:448
	v_cmp_ge_u32_e32 vcc, v189, v190
	v_fmac_f32_e32 v214, 0x3e000000, v76
	v_add_u32_e32 v191, 3, v188
	v_cndmask_b32_e32 v194, v179, v214, vcc
	ds_read_b32 v214, v98 offset:452
	v_cmp_ge_u32_e32 vcc, v189, v191
	v_fmac_f32_e32 v215, 0x3e000000, v77
	v_add_u32_e32 v190, 16, v188
	v_cndmask_b32_e32 v79, v179, v215, vcc
	ds_read_b32 v215, v98 offset:456
	v_cmp_ge_u32_e32 vcc, v189, v190
	v_fmac_f32_e32 v223, 0x3e000000, v70
	v_add_u32_e32 v191, 17, v188
	v_cndmask_b32_e32 v74, v179, v223, vcc
	ds_read_b32 v223, v98 offset:460
	v_cmp_ge_u32_e32 vcc, v189, v191
	v_fmac_f32_e32 v228, 0x3e000000, v71
	v_add_u32_e32 v190, 18, v188
	v_cndmask_b32_e32 v64, v179, v228, vcc
	ds_read_b32 v228, v98 offset:512
	v_cmp_ge_u32_e32 vcc, v189, v190
	v_fmac_f32_e32 v229, 0x3e000000, v72
	v_add_u32_e32 v191, 19, v188
	v_cndmask_b32_e32 v75, v179, v229, vcc
	ds_read_b32 v229, v98 offset:516
	v_cmp_ge_u32_e32 vcc, v189, v191
	v_fmac_f32_e32 v230, 0x3e000000, v73
	v_add_u32_e32 v190, 32, v188
; __device__ __forceinline__ void attn_item(const Ctx& C, int it, int itn, u32x4 (&kv)[4], u32x4 (&vv)[4], u32x4 (&qv)[2]) {
;     ...
;     const int a = 16 * w + fr;
;     float mx = -1e30f;
; #pragma unroll
;     for (int kt = 0; kt < 9; ++kt)
; #pragma unroll
;         for (int rg = 0; rg < 4; ++rg) { const int cidx = 16 * (w + kt) + 4 * quad + rg, rel = cidx - 64 - a, ik = 128 * jb - 64 + cidx;
;             const bool valid = (rel >= -64) && (rel <= 64) && (ik >= 0) && (ik < n);
;             const int bi = rel < -64 ? 0 : (rel > 64 ? 128 : rel + 64);
;             const float s = valid ? sc[kt][rg] * 0.125f + bt[bi] : -1e30f;
;             sc[kt][rg] = s; mx = fmaxf(mx, s); }
;     mx = fmaxf(mx, __shfl_xor(mx, 16)); mx = fmaxf(mx, __shfl_xor(mx, 32));
	v_cndmask_b32_e32 v70, v179, v230, vcc
	ds_read_b32 v230, v98 offset:520
	v_cmp_ge_u32_e32 vcc, v189, v190
	v_fmac_f32_e32 v231, 0x3e000000, v66
	v_add_u32_e32 v191, 33, v188
	v_cndmask_b32_e32 v72, v179, v231, vcc
	ds_read_b32 v231, v98 offset:524
	v_cmp_ge_u32_e32 vcc, v189, v191
	v_fmac_f32_e32 v232, 0x3e000000, v67
	v_add_u32_e32 v190, 34, v188
	v_cndmask_b32_e32 v71, v179, v232, vcc
	v_cmp_ge_u32_e32 vcc, v189, v190
	v_fmac_f32_e32 v233, 0x3e000000, v68
	v_add_u32_e32 v191, 35, v188
	v_cndmask_b32_e32 v73, v179, v233, vcc
	v_cmp_ge_u32_e32 vcc, v189, v191
	v_fmac_f32_e32 v234, 0x3e000000, v69
	v_add_u32_e32 v190, 48, v188
	v_cndmask_b32_e32 v66, v179, v234, vcc
	v_cmp_ge_u32_e32 vcc, v189, v190
	v_fmac_f32_e32 v235, 0x3e000000, v60
	v_add_u32_e32 v191, 49, v188
	v_cndmask_b32_e32 v69, v179, v235, vcc
	v_cmp_ge_u32_e32 vcc, v189, v191
	v_fmac_f32_e32 v236, 0x3e000000, v61
	v_add_u32_e32 v190, 50, v188
	v_cndmask_b32_e32 v67, v179, v236, vcc
	v_cmp_ge_u32_e32 vcc, v189, v190
	v_fmac_f32_e32 v237, 0x3e000000, v62
	v_add_u32_e32 v191, 51, v188
	v_cndmask_b32_e32 v68, v179, v237, vcc
	v_cmp_ge_u32_e32 vcc, v189, v191
	v_fmac_f32_e32 v238, 0x3e000000, v63
	v_add_u32_e32 v190, 64, v188
	v_cndmask_b32_e32 v60, v179, v238, vcc
	v_cmp_ge_u32_e32 vcc, v189, v190
	v_fmac_f32_e32 v240, 0x3e000000, v56
	v_add_u32_e32 v191, 0x41, v188
	v_cndmask_b32_e32 v62, v179, v240, vcc
	v_cmp_ge_u32_e32 vcc, v189, v191
	v_fmac_f32_e32 v241, 0x3e000000, v57
	v_add_u32_e32 v190, 0x42, v188
	v_cndmask_b32_e32 v61, v179, v241, vcc
	v_cmp_ge_u32_e32 vcc, v189, v190
	v_fmac_f32_e32 v242, 0x3e000000, v58
	v_add_u32_e32 v191, 0x43, v188
	v_cndmask_b32_e32 v63, v179, v242, vcc
	v_cmp_ge_u32_e32 vcc, v189, v191
	v_fmac_f32_e32 v243, 0x3e000000, v59
	v_add_u32_e32 v190, 0x50, v188
	v_cndmask_b32_e32 v57, v179, v243, vcc
	v_cmp_ge_u32_e32 vcc, v189, v190
	v_fmac_f32_e32 v244, 0x3e000000, v52
	v_add_u32_e32 v191, 0x51, v188
	v_cndmask_b32_e32 v59, v179, v244, vcc
	v_cmp_ge_u32_e32 vcc, v189, v191
	v_fmac_f32_e32 v245, 0x3e000000, v53
	v_add_u32_e32 v190, 0x52, v188
	v_cndmask_b32_e32 v56, v179, v245, vcc
	v_cmp_ge_u32_e32 vcc, v189, v190
	v_fmac_f32_e32 v246, 0x3e000000, v54
	v_add_u32_e32 v191, 0x53, v188
	v_cndmask_b32_e32 v58, v179, v246, vcc
	v_cmp_ge_u32_e32 vcc, v189, v191
	v_fmac_f32_e32 v247, 0x3e000000, v55
	v_add_u32_e32 v190, 0x60, v188
	v_cndmask_b32_e32 v53, v179, v247, vcc
	v_cmp_ge_u32_e32 vcc, v189, v190
	v_fmac_f32_e32 v248, 0x3e000000, v48
	v_add_u32_e32 v191, 0x61, v188
	v_cndmask_b32_e32 v55, v179, v248, vcc
	v_cmp_ge_u32_e32 vcc, v189, v191
	v_fmac_f32_e32 v249, 0x3e000000, v49
	v_add_u32_e32 v190, 0x62, v188
	v_cndmask_b32_e32 v52, v179, v249, vcc
	v_cmp_ge_u32_e32 vcc, v189, v190
	v_fmac_f32_e32 v250, 0x3e000000, v50
	v_add_u32_e32 v191, 0x63, v188
	v_cndmask_b32_e32 v54, v179, v250, vcc
	s_waitcnt lgkmcnt(0)
	v_cmp_ge_u32_e32 vcc, v189, v191
	v_fmac_f32_e32 v212, 0x3e000000, v51
	v_add_u32_e32 v190, 0x70, v188
	v_cndmask_b32_e32 v49, v179, v212, vcc
	v_cmp_ge_u32_e32 vcc, v189, v190
	v_fmac_f32_e32 v213, 0x3e000000, v44
	v_add_u32_e32 v191, 0x71, v188
	v_cndmask_b32_e32 v50, v179, v213, vcc
	v_cmp_ge_u32_e32 vcc, v189, v191
	v_fmac_f32_e32 v214, 0x3e000000, v45
	v_add_u32_e32 v190, 0x72, v188
	v_cndmask_b32_e32 v48, v179, v214, vcc
	v_cmp_ge_u32_e32 vcc, v189, v190
	v_fmac_f32_e32 v215, 0x3e000000, v46
	v_add_u32_e32 v191, 0x73, v188
	v_cndmask_b32_e32 v45, v179, v215, vcc
	v_cmp_ge_u32_e32 vcc, v189, v191
	v_fmac_f32_e32 v223, 0x3e000000, v47
	v_add_u32_e32 v190, 0x80, v188
	v_cndmask_b32_e32 v44, v179, v223, vcc
	v_cmp_ge_u32_e32 vcc, v189, v190
	v_fmac_f32_e32 v228, 0x3e000000, v40
	v_add_u32_e32 v191, 0x81, v188
	v_cndmask_b32_e32 v47, v179, v228, vcc
	v_cmp_ge_u32_e32 vcc, v189, v191
	v_fmac_f32_e32 v229, 0x3e000000, v41
	v_add_u32_e32 v190, 0x82, v188
	v_cndmask_b32_e32 v46, v179, v229, vcc
	v_cmp_ge_u32_e32 vcc, v189, v190
	v_fmac_f32_e32 v230, 0x3e000000, v42
	v_add_u32_e32 v191, 0x83, v188
	v_cndmask_b32_e32 v51, v179, v230, vcc
	v_cmp_ge_u32_e32 vcc, v189, v191
	v_fmac_f32_e32 v231, 0x3e000000, v43
	s_nop 0
	v_cndmask_b32_e32 v41, v179, v231, vcc
	s_mov_b32 s0, 0xf149f2ca
	v_max3_f32 v40, v195, s0, v91
	v_max3_f32 v40, v40, v194, v79
	v_max3_f32 v40, v40, v74, v64
	v_max3_f32 v40, v40, v75, v70
	v_max3_f32 v40, v40, v72, v71
	v_max3_f32 v40, v40, v73, v66
	v_max3_f32 v40, v40, v69, v67
	v_max3_f32 v40, v40, v68, v60
	v_max3_f32 v40, v40, v62, v61
	v_max3_f32 v40, v40, v63, v57
	v_max3_f32 v40, v40, v59, v56
	v_max3_f32 v40, v40, v58, v53
	v_max3_f32 v40, v40, v55, v52
	v_max3_f32 v40, v40, v54, v49
	v_max3_f32 v40, v40, v50, v48
	v_max3_f32 v40, v40, v45, v44
	v_max3_f32 v40, v40, v47, v46
	v_max3_f32 v40, v40, v51, v41
	ds_bpermute_b32 v42, v169, v40
	s_mov_b32 s1, 0x3fb8aa3b
	s_sub_i32 s0, 5, s52
	s_lshr_b32 s0, s47, s0
	s_waitcnt lgkmcnt(0)
	v_max_f32_e32 v42, v42, v42
	v_max_f32_e32 v40, v40, v42
	ds_bpermute_b32 v42, v170, v40
	s_waitcnt lgkmcnt(0)
; __device__ __forceinline__ unsigned cvt_pk_bf16(float lo, float hi) { f32x2_t v = {lo, hi}; bf2_t r = __builtin_convertvector(v, bf2_t); return __builtin_bit_cast(unsigned, r); }
; __device__ __forceinline__ s16x4_t lds_tr_b64(const bf16_t* p) { return __builtin_amdgcn_ds_read_tr16_b64_v4i16((LAS s16x4_t*)p); }
; __device__ __forceinline__ void attn_item(const Ctx& C, int it, int itn, u32x4 (&kv)[4], u32x4 (&vv)[4], u32x4 (&qv)[2]) {
;     ...
;     float lsum = 0.f;
; #pragma unroll
;     for (int kt = 0; kt < 9; ++kt)
; #pragma unroll
;         for (int rg = 0; rg < 4; ++rg) { const float s = sc[kt][rg]; const float p = (s > -1e29f) ? __expf(s - mx) : 0.f; sc[kt][rg] = p; lsum += p; }
;     lsum += __shfl_xor(lsum, 16); lsum += __shfl_xor(lsum, 32);
;     f32x4 oo[4];
; #pragma unroll
;     for (int dt = 0; dt < 4; ++dt) oo[dt] = (f32x4){0.f, 0.f, 0.f, 0.f};
; #pragma unroll
;     for (int pp = 0; pp < 5; ++pp) { const int ktA = 2 * pp, ktB = 2 * pp + 1, ktBc = ktB < 9 ? ktB : 8;
;         union { bf16x8 v; unsigned u[4]; } pf;
;         pf.u[0] = cvt_pk_bf16(sc[ktA][0], sc[ktA][1]); pf.u[1] = cvt_pk_bf16(sc[ktA][2], sc[ktA][3]);
;         if (ktB < 9) { pf.u[2] = cvt_pk_bf16(sc[ktBc][0], sc[ktBc][1]); pf.u[3] = cvt_pk_bf16(sc[ktBc][2], sc[ktBc][3]); } else { pf.u[2] = 0u; pf.u[3] = 0u; }
; #pragma unroll
;         for (int dt = 0; dt < 4; ++dt) { const bf16_t* vr = Vs + (16 * w + 4 * quad + (fr >> 2)) * 72 + 16 * dt + 4 * (fr & 3);
;             union { bf16x8 v; s16x4_t h[2]; } vf; vf.h[0] = lds_tr_b64(vr + 16 * ktA * 72); vf.h[1] = lds_tr_b64(vr + 16 * ktBc * 72);
;             oo[dt] = __builtin_amdgcn_mfma_f32_16x16x32_bf16(vf.v, pf.v, oo[dt], 0, 0, 0); } }
	v_max_f32_e32 v42, v42, v42
	v_max_f32_e32 v42, v40, v42
	v_mul_f32_e32 v178, 0xbfb8aa3b, v42
	v_fma_f32 v40, v195, s1, v178
	v_fma_f32 v43, v91, s1, v178
	v_exp_f32_e32 v40, v40
	v_exp_f32_e32 v43, v43
	v_add_f32_e32 v76, 0, v40
	s_nop 0
	v_add_f32_e32 v77, v43, v76
	v_fma_f32 v76, v194, s1, v178
	v_exp_f32_e32 v76, v76
	v_cvt_pk_bf16_f32 v196, v40, v43
	s_nop 0
	v_add_f32_e32 v91, v76, v77
	v_fma_f32 v77, v79, s1, v178
	v_exp_f32_e32 v77, v77
	s_nop 1
	v_fma_f32 v74, v74, s1, v178
	v_exp_f32_e32 v74, v74
	v_add_f32_e32 v79, v77, v91
	v_cvt_pk_bf16_f32 v197, v76, v77
	v_fma_f32 v64, v64, s1, v178
	v_exp_f32_e32 v64, v64
	v_add_f32_e32 v91, v74, v79
	v_mov_b32_e32 v79, v64
	v_fma_f32 v75, v75, s1, v178
	v_exp_f32_e32 v75, v75
	v_add_f32_e32 v64, v79, v91
	v_cvt_pk_bf16_f32 v198, v74, v79
	v_fma_f32 v70, v70, s1, v178
	v_exp_f32_e32 v70, v70
	v_add_f32_e32 v64, v75, v64
	v_mov_b32_e32 v91, v70
	v_add_f32_e32 v70, v91, v64
	v_fma_f32 v64, v72, s1, v178
	v_exp_f32_e32 v64, v64
	v_cvt_pk_bf16_f32 v199, v75, v91
	ds_read_b64_tr_b16 v[76:77], v171 offset:57600
	ds_read_b64_tr_b16 v[74:75], v171 offset:55296
	ds_read_b64_tr_b16 v[200:201], v171 offset:55328
	v_add_f32_e32 v72, v64, v70
	v_fma_f32 v70, v71, s1, v178
	v_fma_f32 v71, v73, s1, v178
	v_exp_f32_e32 v70, v70
	v_exp_f32_e32 v71, v71
	ds_read_b64_tr_b16 v[202:203], v171 offset:57632
	v_add_f32_e32 v72, v70, v72
	ds_read_b64_tr_b16 v[204:205], v171 offset:55360
	ds_read_b64_tr_b16 v[206:207], v171 offset:57664
	v_fma_f32 v66, v66, s1, v178
	v_exp_f32_e32 v66, v66
	v_add_f32_e32 v72, v71, v72
	ds_read_b64_tr_b16 v[208:209], v171 offset:55392
	ds_read_b64_tr_b16 v[210:211], v171 offset:57696
	s_waitcnt lgkmcnt(6)
	v_mfma_f32_16x16x32_bf16 v[74:77], v[74:77], v[196:199], 0
	v_fma_f32 v69, v69, s1, v178
	v_exp_f32_e32 v69, v69
	v_add_f32_e32 v72, v66, v72
	s_waitcnt lgkmcnt(4)
	v_mfma_f32_16x16x32_bf16 v[200:203], v[200:203], v[196:199], 0
	v_mov_b32_e32 v91, v65
	v_fma_f32 v67, v67, s1, v178
	v_exp_f32_e32 v67, v67
	v_add_f32_e32 v72, v69, v72
	s_waitcnt lgkmcnt(2)
	v_mfma_f32_16x16x32_bf16 v[204:207], v[204:207], v[196:199], 0
	v_fma_f32 v68, v68, s1, v178
	v_exp_f32_e32 v68, v68
	v_add_f32_e32 v72, v67, v72
	s_waitcnt lgkmcnt(0)
	v_mfma_f32_16x16x32_bf16 v[196:199], v[208:211], v[196:199], 0
	v_cvt_pk_bf16_f32 v209, v71, v66
	v_fma_f32 v60, v60, s1, v178
	v_exp_f32_e32 v60, v60
	v_add_f32_e32 v73, v68, v72
	v_cvt_pk_bf16_f32 v210, v69, v67
	v_cvt_pk_bf16_f32 v208, v64, v70
	v_mov_b32_e32 v72, v60
	v_fma_f32 v60, v62, s1, v178
	v_exp_f32_e32 v60, v60
	v_add_f32_e32 v73, v72, v73
	v_cvt_pk_bf16_f32 v211, v68, v72
	v_fma_f32 v61, v61, s1, v178
	v_exp_f32_e32 v61, v61
	v_add_f32_e32 v62, v60, v73
	ds_read_b64_tr_b16 v[66:67], v171 offset:59904
	ds_read_b64_tr_b16 v[68:69], v171 offset:62208
	s_waitcnt lgkmcnt(0)
	v_mfma_f32_16x16x32_bf16 v[66:69], v[66:69], v[208:211], v[74:77]
	v_add_f32_e32 v73, v61, v62
	v_fma_f32 v62, v63, s1, v178
	v_exp_f32_e32 v62, v62
	ds_read_b64_tr_b16 v[74:75], v171 offset:59936
	ds_read_b64_tr_b16 v[76:77], v171 offset:62240
	s_waitcnt lgkmcnt(0)
	v_mfma_f32_16x16x32_bf16 v[74:77], v[74:77], v[208:211], v[200:203]
	v_fma_f32 v57, v57, s1, v178
	v_exp_f32_e32 v57, v57
	v_add_f32_e32 v63, v62, v73
	ds_read_b64_tr_b16 v[200:201], v171 offset:59968
	ds_read_b64_tr_b16 v[202:203], v171 offset:62272
	s_waitcnt lgkmcnt(0)
	v_mfma_f32_16x16x32_bf16 v[200:203], v[200:203], v[208:211], v[204:207]
	v_fma_f32 v59, v59, s1, v178
	v_exp_f32_e32 v59, v59
	v_add_f32_e32 v63, v57, v63
	ds_read_b64_tr_b16 v[204:205], v171 offset:60000
	ds_read_b64_tr_b16 v[206:207], v171 offset:62304
	v_cvt_pk_bf16_f32 v60, v60, v61
	v_fma_f32 v56, v56, s1, v178
	v_exp_f32_e32 v56, v56
	v_add_f32_e32 v63, v59, v63
	v_cvt_pk_bf16_f32 v61, v62, v57
	s_waitcnt lgkmcnt(0)
	v_mfma_f32_16x16x32_bf16 v[196:199], v[204:207], v[208:211], v[196:199]
	v_fma_f32 v58, v58, s1, v178
	v_exp_f32_e32 v58, v58
	v_add_f32_e32 v63, v56, v63
	v_cvt_pk_bf16_f32 v62, v59, v56
	v_mov_b32_e32 v64, v65
	v_fma_f32 v53, v53, s1, v178
	v_exp_f32_e32 v53, v53
	v_add_f32_e32 v73, v58, v63
	v_mov_b32_e32 v63, v53
	v_fma_f32 v53, v55, s1, v178
	v_exp_f32_e32 v53, v53
	v_add_f32_e32 v73, v63, v73
	v_cvt_pk_bf16_f32 v63, v58, v63
	v_fma_f32 v52, v52, s1, v178
	v_exp_f32_e32 v52, v52
	ds_read_b64_tr_b16 v[56:57], v171 offset:64512
	ds_read_b64_tr_b16 v[58:59], v172 offset:11520
	ds_read_b64_tr_b16 v[70:71], v172 offset:11552
	v_add_f32_e32 v55, v53, v73
	s_waitcnt lgkmcnt(1)
	v_mfma_f32_16x16x32_bf16 v[56:59], v[56:59], v[60:63], v[66:69]
	v_fma_f32 v54, v54, s1, v178
	v_exp_f32_e32 v54, v54
	v_add_f32_e32 v55, v52, v55
	ds_read_b64_tr_b16 v[68:69], v171 offset:64544
	s_waitcnt lgkmcnt(0)
	v_mfma_f32_16x16x32_bf16 v[66:69], v[68:71], v[60:63], v[74:77]
	v_fma_f32 v49, v49, s1, v178
	v_exp_f32_e32 v49, v49
	v_add_f32_e32 v55, v54, v55
	ds_read_b64_tr_b16 v[74:75], v171 offset:64576
	ds_read_b64_tr_b16 v[76:77], v172 offset:11584
	s_waitcnt lgkmcnt(0)
	v_mfma_f32_16x16x32_bf16 v[74:77], v[74:77], v[60:63], v[200:203]
	v_fma_f32 v50, v50, s1, v178
	v_exp_f32_e32 v50, v50
	v_add_f32_e32 v55, v49, v55
	ds_read_b64_tr_b16 v[200:201], v171 offset:64608
	ds_read_b64_tr_b16 v[202:203], v172 offset:11616
	v_cvt_pk_bf16_f32 v52, v53, v52
	v_fma_f32 v48, v48, s1, v178
	v_exp_f32_e32 v48, v48
	v_add_f32_e32 v73, v50, v55
	v_cvt_pk_bf16_f32 v53, v54, v49
	s_waitcnt lgkmcnt(0)
; __device__ __forceinline__ unsigned cvt_pk_bf16(float lo, float hi) { f32x2_t v = {lo, hi}; bf2_t r = __builtin_convertvector(v, bf2_t); return __builtin_bit_cast(unsigned, r); }
; __device__ __forceinline__ s16x4_t lds_tr_b64(const bf16_t* p) { return __builtin_amdgcn_ds_read_tr16_b64_v4i16((LAS s16x4_t*)p); }
;     __device__ __forceinline__ float* fp(size_t off) const { return (float*)(ws + off); }
; __device__ __forceinline__ void attn_item(const Ctx& C, int it, int itn, u32x4 (&kv)[4], u32x4 (&vv)[4], u32x4 (&qv)[2]) {
;     ...
; #pragma unroll
;     for (int pp = 0; pp < 5; ++pp) { const int ktA = 2 * pp, ktB = 2 * pp + 1, ktBc = ktB < 9 ? ktB : 8;
;         union { bf16x8 v; unsigned u[4]; } pf;
;         pf.u[0] = cvt_pk_bf16(sc[ktA][0], sc[ktA][1]); pf.u[1] = cvt_pk_bf16(sc[ktA][2], sc[ktA][3]);
;         if (ktB < 9) { pf.u[2] = cvt_pk_bf16(sc[ktBc][0], sc[ktBc][1]); pf.u[3] = cvt_pk_bf16(sc[ktBc][2], sc[ktBc][3]); } else { pf.u[2] = 0u; pf.u[3] = 0u; }
; #pragma unroll
;         for (int dt = 0; dt < 4; ++dt) { const bf16_t* vr = Vs + (16 * w + 4 * quad + (fr >> 2)) * 72 + 16 * dt + 4 * (fr & 3);
;             union { bf16x8 v; s16x4_t h[2]; } vf; vf.h[0] = lds_tr_b64(vr + 16 * ktA * 72); vf.h[1] = lds_tr_b64(vr + 16 * ktBc * 72);
;             oo[dt] = __builtin_amdgcn_mfma_f32_16x16x32_bf16(vf.v, pf.v, oo[dt], 0, 0, 0); } }
;     const float inv = 1.0f / lsum;
;     const size_t tok = (size_t)(b * SEQ + r + dil * (128 * jb + a));
;     __syncthreads();
; #pragma unroll
;     for (int dt = 0; dt < 4; ++dt) { u32x2 o; o.x = cvt_pk_bf16(oo[dt][0] * inv, oo[dt][1] * inv); o.y = cvt_pk_bf16(oo[dt][2] * inv, oo[dt][3] * inv);
;         *(u32x2*)(pd + tok * 2304 + hq * 64 + 16 * dt + 4 * quad) = o; }
;     if (quad == 0) C.fp(OFF_LSE)[((size_t)g * M_TOK + tok) * 4 + (hq & 3)] = mx + __logf(lsum);
	v_mfma_f32_16x16x32_bf16 v[60:63], v[200:203], v[60:63], v[196:199]
	v_mov_b32_e32 v55, v48
	v_fma_f32 v45, v45, s1, v178
	v_exp_f32_e32 v45, v45
	v_add_f32_e32 v48, v55, v73
	v_cvt_pk_bf16_f32 v54, v50, v55
	v_mov_b32_e32 v73, v45
	v_fma_f32 v44, v44, s1, v178
	v_exp_f32_e32 v44, v44
	v_add_f32_e32 v45, v73, v48
	v_mov_b32_e32 v194, v44
	v_add_f32_e32 v44, v194, v45
	v_fma_f32 v45, v47, s1, v178
	v_cvt_pk_bf16_f32 v55, v73, v194
	ds_read_b64_tr_b16 v[70:71], v172 offset:13824
	ds_read_b64_tr_b16 v[72:73], v172 offset:16128
	v_exp_f32_e32 v45, v45
	s_waitcnt lgkmcnt(0)
	v_mfma_f32_16x16x32_bf16 v[56:59], v[70:73], v[52:55], v[56:59]
	ds_read_b64_tr_b16 v[70:71], v172 offset:13856
	ds_read_b64_tr_b16 v[72:73], v172 offset:16160
	v_fma_f32 v46, v46, s1, v178
	v_fma_f32 v47, v51, s1, v178
	v_exp_f32_e32 v46, v46
	v_exp_f32_e32 v47, v47
	s_waitcnt lgkmcnt(0)
	v_mfma_f32_16x16x32_bf16 v[66:69], v[70:73], v[52:55], v[66:69]
	ds_read_b64_tr_b16 v[70:71], v172 offset:13888
	ds_read_b64_tr_b16 v[72:73], v172 offset:16192
	s_waitcnt lgkmcnt(0)
	v_mfma_f32_16x16x32_bf16 v[70:73], v[70:73], v[52:55], v[74:77]
	v_fma_f32 v41, v41, s1, v178
	v_exp_f32_e32 v41, v41
	ds_read_b64_tr_b16 v[74:75], v172 offset:13920
	ds_read_b64_tr_b16 v[76:77], v172 offset:16224
	v_add_f32_e32 v44, v45, v44
	v_add_f32_e32 v44, v46, v44
	v_mov_b32_e32 v48, v41
	v_add_f32_e32 v44, v47, v44
	s_waitcnt lgkmcnt(0)
	v_mfma_f32_16x16x32_bf16 v[50:53], v[74:77], v[52:55], v[60:63]
	v_add_f32_e32 v41, v48, v44
	ds_bpermute_b32 v44, v169, v41
	ds_read_b64_tr_b16 v[54:55], v172 offset:18464
	v_cvt_pk_bf16_f32 v62, v45, v46
	v_cvt_pk_bf16_f32 v63, v47, v48
	ds_read_b64_tr_b16 v[46:47], v172 offset:18432
	s_waitcnt lgkmcnt(2)
	v_add_f32_e32 v41, v41, v44
	ds_bpermute_b32 v44, v170, v41
	s_lshl_b32 s1, s51, 12
	s_or_b32 s0, s0, s1
	s_waitcnt lgkmcnt(1)
	v_mov_b32_e32 v48, v46
	v_mov_b32_e32 v49, v47
	s_waitcnt lgkmcnt(0)
	v_add_f32_e32 v41, v41, v44
	v_div_scale_f32 v40, s[48:49], v41, v41, 1.0
	v_mfma_f32_16x16x32_bf16 v[46:49], v[46:49], v[62:65], v[56:59]
	v_rcp_f32_e32 v43, v40
	s_nop 1
	v_mov_b32_e32 v56, v54
	v_mov_b32_e32 v57, v55
	ds_read_b64_tr_b16 v[58:59], v172 offset:18496
	v_fma_f32 v44, -v40, v43, 1.0
	v_mfma_f32_16x16x32_bf16 v[54:57], v[54:57], v[62:65], v[66:69]
	v_fmac_f32_e32 v43, v44, v43
	s_nop 1
	ds_read_b64_tr_b16 v[66:67], v172 offset:18528
	s_waitcnt lgkmcnt(1)
	v_mov_b32_e32 v60, v58
	v_mov_b32_e32 v61, v59
	v_div_scale_f32 v44, vcc, 1.0, v41, 1.0
	s_waitcnt lgkmcnt(0)
	v_mov_b32_e32 v68, v66
	v_mov_b32_e32 v69, v67
	v_mul_f32_e32 v45, v44, v43
	v_mfma_f32_16x16x32_bf16 v[58:61], v[58:61], v[62:65], v[70:73]
	s_barrier
	v_mfma_f32_16x16x32_bf16 v[50:53], v[66:69], v[62:65], v[50:53]
	v_fma_f32 v62, -v40, v45, v44
	v_fmac_f32_e32 v45, v62, v43
	v_fma_f32 v40, -v40, v45, v44
	v_div_fmas_f32 v40, v40, v43, v45
	v_div_fixup_f32 v44, v40, v41, 1.0
	v_add_u32_e32 v40, s46, v83
	v_lshlrev_b32_e32 v40, s52, v40
	v_add_u32_e32 v40, s0, v40
	v_mov_b64_e32 v[62:63], s[42:43]
	v_mad_i64_i32 v[62:63], s[0:1], v40, s66, v[62:63]
	s_lshl_b32 s0, s41, 6
	s_ashr_i32 s1, s0, 31
	v_lshl_add_u64 v[62:63], s[0:1], 1, v[62:63]
	v_pk_mul_f32 v[46:47], v[44:45], v[46:47] op_sel_hi:[0,1]
	v_pk_mul_f32 v[48:49], v[44:45], v[48:49] op_sel_hi:[0,1]
	v_lshl_add_u64 v[62:63], v[62:63], 0, v[90:91]
	v_cvt_pk_bf16_f32 v46, v46, v47
	v_cvt_pk_bf16_f32 v47, v48, v49
	global_store_dwordx2 v[62:63], v[46:47], off
	v_pk_mul_f32 v[46:47], v[44:45], v[54:55] op_sel_hi:[0,1]
	v_pk_mul_f32 v[48:49], v[44:45], v[56:57] op_sel_hi:[0,1]
	v_cvt_pk_bf16_f32 v46, v46, v47
	v_cvt_pk_bf16_f32 v47, v48, v49
	global_store_dwordx2 v[62:63], v[46:47], off offset:32
	v_pk_mul_f32 v[46:47], v[44:45], v[58:59] op_sel_hi:[0,1]
	v_pk_mul_f32 v[48:49], v[44:45], v[60:61] op_sel_hi:[0,1]
	v_cvt_pk_bf16_f32 v46, v46, v47
	v_cvt_pk_bf16_f32 v47, v48, v49
	global_store_dwordx2 v[62:63], v[46:47], off offset:64
	v_pk_mul_f32 v[46:47], v[44:45], v[50:51] op_sel_hi:[0,1]
	v_pk_mul_f32 v[44:45], v[44:45], v[52:53] op_sel_hi:[0,1]
	v_cvt_pk_bf16_f32 v46, v46, v47
	v_cvt_pk_bf16_f32 v47, v44, v45
	global_store_dwordx2 v[62:63], v[46:47], off offset:96
	s_and_saveexec_b64 s[0:1], s[20:21]
	s_cbranch_execz .LBB0_344
	v_cmp_gt_f32_e32 vcc, s54, v41
	s_ashr_i32 s41, s40, 31
	s_lshl_b64 s[40:41], s[40:41], 19
	v_cndmask_b32_e64 v43, 0, 32, vcc
	v_ldexp_f32 v41, v41, v43
	v_log_f32_e32 v43, v41
	v_readlane_b32 s46, v255, 43
	v_cndmask_b32_e32 v44, 0, v225, vcc
	s_add_u32 s40, s46, s40
	v_mul_f32_e32 v45, 0x3f317217, v43
	v_fma_f32 v45, v43, s56, -v45
	v_fmac_f32_e32 v45, 0x3377d1cf, v43
	v_fmac_f32_e32 v45, 0x3f317217, v43
	v_cmp_lt_f32_e64 vcc, |v43|, s57
	v_readlane_b32 s46, v255, 44
	v_ashrrev_i32_e32 v41, 31, v40
	v_cndmask_b32_e32 v43, v43, v45, vcc
	s_addc_u32 s41, s46, s41
	s_lshr_b32 s36, s36, 3
	v_sub_f32_e32 v43, v43, v44
	v_lshl_add_u64 v[40:41], v[40:41], 4, s[40:41]
	s_and_b32 s36, s36, 12
	v_add_f32_e32 v42, v42, v43
	v_lshl_add_u64 v[40:41], v[40:41], 0, s[36:37]
	global_store_dword v[40:41], v42, off
	s_branch .LBB0_344
